# q8b + packed v_pk_add_f32 split into scalar v_add_f32 pairs in the sample FoX unit loops (packed f32 beside MFMAs is slow)
# speedup vs baseline: 1.0190x; 1.0021x over previous
; template <int KIND>
; __device__ __forceinline__ void sample_unit(const AttnCtx& C, int u, LAS unsigned char* lds) {
;     ...
;         if (wid == 0) {
;             float loc[4]; float run = 0.f;
; #pragma unroll
;             for (int j = 0; j < 4; ++j) { const int c = 63 - (4 * lane + j); const float v = (c >= 0) ? tot[c] : 0.f; run += v; loc[j] = run; }
;             float incl = run;
; #pragma unroll
;             for (int o = 1; o < 64; o <<= 1) { const float t = __shfl_up(incl, o); if (lane >= o) incl += t; }
;             const float excl = incl - run;
; #pragma unroll
;             for (int j = 0; j < 4; ++j) { const int c = 63 - (4 * lane + j); if (c >= 0) dd[c] = -(excl + loc[j]); }
;             if (lane == 0) dd[64] = 0.f;
.LBB0_378:
	s_or_b64 exec, exec, s[2:3]
	s_and_saveexec_b64 s[2:3], vcc
	v_or_b32_e32 v2, 1, v1
	v_sub_u32_e32 v2, 63, v2
	v_lshl_add_u32 v2, v2, 2, 0
	v_add_u32_e32 v2, 0x22400, v2
	ds_read_b32 v4, v2
	s_or_b64 exec, exec, s[2:3]
	v_mov_b32_e32 v6, 0
	v_mov_b32_e32 v7, 0
	s_and_saveexec_b64 s[2:3], vcc
	v_or_b32_e32 v2, 2, v1
	v_sub_u32_e32 v2, 63, v2
	v_lshl_add_u32 v2, v2, 2, 0
	v_add_u32_e32 v2, 0x22400, v2
	ds_read_b32 v7, v2
	s_or_b64 exec, exec, s[2:3]
	v_or_b32_e32 v2, 3, v1
	v_sub_u32_e32 v2, 63, v2
	v_lshl_add_u32 v2, v2, 2, 0
	s_and_saveexec_b64 s[2:3], vcc
	v_add_u32_e32 v6, 0x22400, v2
	ds_read_b32 v6, v6
	s_or_b64 exec, exec, s[2:3]
	v_and_b32_e32 v9, 64, v234
	v_add_u32_e32 v8, -1, v234
	s_waitcnt lgkmcnt(0)
	v_add_f32_e32 v4, v5, v4
	v_cmp_lt_i32_e64 s[2:3], v8, v9
	v_add_f32_e32 v7, v4, v7
	v_add_f32_e32 v6, v7, v6
	v_cndmask_b32_e64 v8, v8, v234, s[2:3]
	v_lshlrev_b32_e32 v8, 2, v8
	ds_bpermute_b32 v8, v8, v6
	v_add_u32_e32 v10, -2, v234
	v_cmp_lt_i32_e64 s[4:5], v10, v9
	v_cmp_eq_u32_e64 s[2:3], 0, v35
	s_waitcnt lgkmcnt(0)
	v_add_f32_e32 v8, v6, v8
	v_cndmask_b32_e64 v10, v10, v234, s[4:5]
	v_cndmask_b32_e64 v8, v8, v6, s[2:3]
	v_lshlrev_b32_e32 v10, 2, v10
	ds_bpermute_b32 v10, v10, v8
	v_cmp_gt_u32_e64 s[4:5], 2, v35
	s_waitcnt lgkmcnt(0)
	v_add_f32_e32 v10, v8, v10
	v_cndmask_b32_e64 v8, v10, v8, s[4:5]
	v_add_u32_e32 v10, -4, v234
	v_cmp_lt_i32_e64 s[4:5], v10, v9
	s_nop 1
	v_cndmask_b32_e64 v10, v10, v234, s[4:5]
	v_lshlrev_b32_e32 v10, 2, v10
	ds_bpermute_b32 v10, v10, v8
	v_cmp_gt_u32_e64 s[4:5], 4, v35
	s_waitcnt lgkmcnt(0)
	v_add_f32_e32 v10, v8, v10
	v_cndmask_b32_e64 v8, v10, v8, s[4:5]
	v_add_u32_e32 v10, -8, v234
	v_cmp_lt_i32_e64 s[4:5], v10, v9
	s_nop 1
	v_cndmask_b32_e64 v9, v10, v234, s[4:5]
	v_lshlrev_b32_e32 v9, 2, v9
	ds_bpermute_b32 v9, v9, v8
	s_and_saveexec_b64 s[4:5], vcc
	s_cbranch_execz .LBB0_386
	s_waitcnt lgkmcnt(0)
	v_add_f32_e32 v9, v8, v9
	v_cmp_gt_u32_e32 vcc, 8, v35
	v_add_u32_e32 v2, 0x22580, v2
	s_nop 0
	v_cndmask_b32_e32 v8, v9, v8, vcc
	v_sub_f32_e32 v10, v8, v6
	v_add_f32_e32 v4, v4, v10
	v_add_f32_e32 v5, v5, v10
	s_nop 0
	v_xor_b32_e32 v9, 0x80000000, v5
	v_xor_b32_e32 v8, 0x80000000, v4
	v_add_f32_e32 v4, v6, v10
	v_add_f32_e32 v5, v7, v10
	s_nop 0
	v_xor_b32_e32 v7, 0x80000000, v5
	v_xor_b32_e32 v6, 0x80000000, v4
	ds_write_b128 v2, v[6:9]

; #define LAS __attribute__((address_space(3)))
; __device__ __forceinline__ unsigned pk2(float lo, float hi) { f32x2_t v = {lo, hi}; bf16x2_t b = __builtin_convertvector(v, bf16x2_t); return __builtin_bit_cast(unsigned, b); }
; __device__ __forceinline__ s16x4 vtr(const LAS unsigned char* p) { return __builtin_bit_cast(s16x4, __builtin_amdgcn_ds_read_tr16_b64_v4i16((LAS v4i16_t*)p)); }
; template <int KIND>
; __device__ __forceinline__ void sample_unit(const AttnCtx& C, int u, LAS unsigned char* lds) {
;     ...
;         float rs = 0.f;
; #pragma unroll
;         for (int r = 0; r < 16; ++r) { p0[r] = __builtin_amdgcn_exp2f(p0[r] - m_run); p1[r] = __builtin_amdgcn_exp2f(p1[r] - m_run); rs += p0[r] + p1[r]; }
;         l_run += rs;
;         v4u pw[4];
;         pw[0] = (v4u){pk2(p0[0], p0[1]), pk2(p0[2], p0[3]), pk2(p0[4], p0[5]), pk2(p0[6], p0[7])};
;         pw[1] = (v4u){pk2(p0[8], p0[9]), pk2(p0[10], p0[11]), pk2(p0[12], p0[13]), pk2(p0[14], p0[15])};
;         pw[2] = (v4u){pk2(p1[0], p1[1]), pk2(p1[2], p1[3]), pk2(p1[4], p1[5]), pk2(p1[6], p1[7])};
;         pw[3] = (v4u){pk2(p1[8], p1[9]), pk2(p1[10], p1[11]), pk2(p1[12], p1[13]), pk2(p1[14], p1[15])};
;         if (!hasv) {
;             LAS unsigned char* vw = lds + bufi * SBUF + 32768 + j * 8192;
;             const int q16_ = lane & 15, c_ = q16_ >> 1;
; #pragma unroll
;             for (int i = 0; i < 16; ++i) { const int key = 4 * i + (lane >> 4); const f32x4 f_ = __builtin_bit_cast(f32x4, tv[i]);
;                 *(LAS u32x2_t*)(vw + (c_ >> 2) * 4096 + (key >> 4) * 1024 + (key & 15) * 64 + (c_ & 3) * 16 + (q16_ & 1) * 8) = (u32x2_t){pk2(f_[0], f_[1]), pk2(f_[2], f_[3])}; }
;             asm volatile("s_waitcnt lgkmcnt(0)" ::: "memory");
;         }
;         const LAS unsigned char* vp = vt + ((lane >> 4) & 1) * 32 + (lane & 3) * 8 + (4 * hi + ((lane & 15) >> 2)) * 64;
; #pragma unroll
;         for (int d = 0; d < NDB; ++d)
; #pragma unroll
;             for (int ks = 0; ks < 4; ++ks) {
;                 const s16x4 lo = vtr(vp + d * 4096 + ks * 1024), hh = vtr(vp + d * 4096 + ks * 1024 + 512);
;                 const bf16x8 vf = (bf16x8){lo[0], lo[1], lo[2], lo[3], hh[0], hh[1], hh[2], hh[3]};
;                 o[d] = __builtin_amdgcn_mfma_f32_32x32x16_bf16(__builtin_bit_cast(bf16x8, pw[ks]), vf, o[d], 0, 0, 0);
;             }
.LBB0_402:
	v_sub_f32_e32 v15, v114, v218
	v_exp_f32_e32 v50, v15
	v_sub_f32_e32 v15, v115, v218
	v_sub_f32_e32 v2, v2, v218
	v_exp_f32_e32 v129, v15
	v_exp_f32_e32 v16, v2
	v_sub_f32_e32 v2, v113, v218
	v_exp_f32_e32 v2, v2
	v_add_f32_e32 v17, v50, v129
	v_sub_f32_e32 v15, v111, v218
	v_sub_f32_e32 v13, v13, v218
	v_add_f32_e32 v44, v16, v2
	v_add_f32_e32 v45, v17, v3
	v_exp_f32_e32 v17, v15
	v_sub_f32_e32 v15, v112, v218
	v_exp_f32_e32 v130, v15
	v_sub_f32_e32 v15, v109, v218
	v_add_f32_e32 v114, v44, v44
	v_add_f32_e32 v115, v44, v45
	v_exp_f32_e32 v44, v15
	v_sub_f32_e32 v15, v110, v218
	v_exp_f32_e32 v114, v15
	v_add_f32_e32 v45, v17, v130
	v_sub_f32_e32 v15, v107, v218
	v_exp_f32_e32 v118, v13
	v_add_f32_e32 v46, v44, v114
	v_add_f32_e32 v47, v45, v115
	v_exp_f32_e32 v45, v15
	v_sub_f32_e32 v15, v108, v218
	v_exp_f32_e32 v115, v15
	v_sub_f32_e32 v15, v105, v218
	v_add_f32_e32 v110, v46, v46
	v_add_f32_e32 v111, v46, v47
	v_exp_f32_e32 v46, v15
	v_sub_f32_e32 v15, v106, v218
	v_exp_f32_e32 v110, v15
	v_add_f32_e32 v47, v45, v115
	v_sub_f32_e32 v15, v103, v218
	v_sub_f32_e32 v13, v14, v218
	v_add_f32_e32 v48, v46, v110
	v_add_f32_e32 v49, v47, v111
	v_exp_f32_e32 v47, v15
	v_sub_f32_e32 v15, v104, v218
	v_exp_f32_e32 v103, v15
	v_sub_f32_e32 v15, v42, v218
	v_add_f32_e32 v108, v48, v48
	v_add_f32_e32 v109, v48, v49
	v_exp_f32_e32 v42, v15
	v_sub_f32_e32 v15, v43, v218
	v_exp_f32_e32 v108, v15
	v_add_f32_e32 v43, v47, v103
	v_sub_f32_e32 v15, v40, v218
	v_sub_f32_e32 v11, v11, v218
	v_add_f32_e32 v48, v42, v108
	v_add_f32_e32 v49, v43, v109
	v_exp_f32_e32 v43, v15
	v_sub_f32_e32 v15, v41, v218
	v_exp_f32_e32 v109, v15
	v_sub_f32_e32 v15, v38, v218
	v_add_f32_e32 v112, v48, v48
	v_add_f32_e32 v113, v48, v49
	v_exp_f32_e32 v38, v15
	v_sub_f32_e32 v15, v39, v218
	v_exp_f32_e32 v112, v15
	v_add_f32_e32 v39, v43, v109
	v_sub_f32_e32 v15, v36, v218
	v_exp_f32_e32 v111, v15
	v_add_f32_e32 v40, v38, v112
	v_add_f32_e32 v41, v39, v113
	v_sub_f32_e32 v15, v37, v218
	v_add_f32_e32 v116, v40, v40
	v_add_f32_e32 v117, v40, v41
	v_exp_f32_e32 v131, v15
	v_exp_f32_e32 v116, v13
	v_exp_f32_e32 v113, v11
	v_sub_f32_e32 v11, v12, v218
	v_add_f32_e32 v119, v111, v131
	v_add_f32_e32 v14, v118, v116
	v_add_f32_e32 v15, v119, v117
	v_sub_f32_e32 v9, v9, v218
	v_add_f32_e32 v120, v14, v14
	v_add_f32_e32 v121, v14, v15
	v_exp_f32_e32 v117, v11
	v_exp_f32_e32 v122, v9
	v_sub_f32_e32 v9, v10, v218
	v_exp_f32_e32 v120, v9
	v_add_f32_e32 v123, v113, v117
	v_lshlrev_b32_e32 v12, 4, v35
	v_sub_f32_e32 v7, v7, v218
	v_add_f32_e32 v10, v122, v120
	v_add_f32_e32 v11, v123, v121
	v_and_b32_e32 v12, 0xc0, v12
	v_add_f32_e32 v126, v10, v10
	v_add_f32_e32 v127, v10, v11
	v_lshlrev_b32_e32 v10, 1, v35
	v_lshlrev_b32_e32 v11, 3, v35
	v_and_b32_e32 v10, 32, v10
	v_and_b32_e32 v11, 24, v11
	v_add3_u32 v10, 0, v10, v11
	v_lshlrev_b32_e32 v11, 8, v132
	v_exp_f32_e32 v119, v7
	v_sub_f32_e32 v7, v8, v218
	v_add3_u32 v123, v10, v11, v12
	v_exp_f32_e32 v121, v7
	v_sub_f32_e32 v14, v6, v218
	v_cvt_pk_bf16_f32 v6, v50, v16
	v_cvt_pk_bf16_f32 v7, v17, v44
	v_cvt_pk_bf16_f32 v8, v45, v46
	v_cvt_pk_bf16_f32 v9, v47, v42
	ds_read_b64_tr_b16 v[10:11], v123 offset:32768
	ds_read_b64_tr_b16 v[12:13], v123 offset:33280
	v_exp_f32_e32 v128, v14
	v_cvt_pk_bf16_f32 v14, v43, v38
	s_waitcnt lgkmcnt(0)
	v_mfma_f32_32x32x16_bf16 v[36:51], v[6:9], v[10:13], v[18:33]
	ds_read_b64_tr_b16 v[104:105], v123 offset:33792
	ds_read_b64_tr_b16 v[106:107], v123 offset:34304
	v_cvt_pk_bf16_f32 v15, v111, v118
	v_cvt_pk_bf16_f32 v16, v113, v122
	v_cvt_pk_bf16_f32 v17, v119, v128
	v_cvt_pk_bf16_f32 v10, v129, v2
	v_cvt_pk_bf16_f32 v11, v130, v114
	v_cvt_pk_bf16_f32 v12, v115, v110
	s_waitcnt lgkmcnt(0)
	v_mfma_f32_32x32x16_bf16 v[36:51], v[14:17], v[104:107], v[36:51]
	v_cvt_pk_bf16_f32 v13, v103, v108
	ds_read_b64_tr_b16 v[104:105], v123 offset:34816
	ds_read_b64_tr_b16 v[106:107], v123 offset:35328
	v_sub_f32_e32 v4, v4, v218
	v_exp_f32_e32 v126, v4
	v_cvt_pk_bf16_f32 v108, v109, v112
	ds_read_b64_tr_b16 v[112:113], v123 offset:35840
	ds_read_b64_tr_b16 v[114:115], v123 offset:36352
	v_cvt_pk_bf16_f32 v109, v131, v116
	s_waitcnt lgkmcnt(2)
	v_mfma_f32_32x32x16_bf16 v[36:51], v[10:13], v[104:107], v[36:51]
	v_cvt_pk_bf16_f32 v110, v117, v120
	v_cvt_pk_bf16_f32 v111, v121, v126
	v_add_f32_e32 v129, v119, v121
	s_waitcnt lgkmcnt(0)
	v_mfma_f32_32x32x16_bf16 v[36:51], v[108:111], v[112:115], v[36:51]
	ds_read_b64_tr_b16 v[104:105], v123 offset:36864
	ds_read_b64_tr_b16 v[106:107], v123 offset:37376
	ds_read_b64_tr_b16 v[112:113], v123 offset:37888
	ds_read_b64_tr_b16 v[114:115], v123 offset:38400
	s_waitcnt lgkmcnt(2)
	v_mfma_f32_32x32x16_bf16 v[18:33], v[6:9], v[104:107], v[18:33]
	s_waitcnt lgkmcnt(0)
	v_mfma_f32_32x32x16_bf16 v[18:33], v[14:17], v[112:115], v[18:33]
	ds_read_b64_tr_b16 v[6:7], v123 offset:38912
	ds_read_b64_tr_b16 v[8:9], v123 offset:39424
	ds_read_b64_tr_b16 v[14:15], v123 offset:39936
	ds_read_b64_tr_b16 v[16:17], v123 offset:40448
	s_waitcnt lgkmcnt(2)
	v_mfma_f32_32x32x16_bf16 v[18:33], v[10:13], v[6:9], v[18:33]
	v_add_f32_e64 v6, v128, v126
	v_add_f32_e64 v7, v129, v127
	v_add_f32_e32 v2, v6, v7
	v_add_f32_e32 v210, v5, v2
	s_waitcnt lgkmcnt(0)
	v_mfma_f32_32x32x16_bf16 v[18:33], v[108:111], v[14:17], v[18:33]

; #define LAS __attribute__((address_space(3)))
; __device__ __forceinline__ unsigned pk2(float lo, float hi) { f32x2_t v = {lo, hi}; bf16x2_t b = __builtin_convertvector(v, bf16x2_t); return __builtin_bit_cast(unsigned, b); }
; template <int KIND>
; __device__ __forceinline__ void sample_unit(const AttnCtx& C, int u, LAS unsigned char* lds) {
;     ...
;         float rs = 0.f;
; #pragma unroll
;         for (int r = 0; r < 16; ++r) { p0[r] = __builtin_amdgcn_exp2f(p0[r] - m_run); p1[r] = __builtin_amdgcn_exp2f(p1[r] - m_run); rs += p0[r] + p1[r]; }
;         l_run += rs;
;         v4u pw[4];
;         pw[0] = (v4u){pk2(p0[0], p0[1]), pk2(p0[2], p0[3]), pk2(p0[4], p0[5]), pk2(p0[6], p0[7])};
;         pw[1] = (v4u){pk2(p0[8], p0[9]), pk2(p0[10], p0[11]), pk2(p0[12], p0[13]), pk2(p0[14], p0[15])};
;         pw[2] = (v4u){pk2(p1[0], p1[1]), pk2(p1[2], p1[3]), pk2(p1[4], p1[5]), pk2(p1[6], p1[7])};
;         pw[3] = (v4u){pk2(p1[8], p1[9]), pk2(p1[10], p1[11]), pk2(p1[12], p1[13]), pk2(p1[14], p1[15])};
;         if (!hasv) {
;             LAS unsigned char* vw = lds + bufi * SBUF + 32768 + j * 8192;
;             const int q16_ = lane & 15, c_ = q16_ >> 1;
; #pragma unroll
;             for (int i = 0; i < 16; ++i) { const int key = 4 * i + (lane >> 4); const f32x4 f_ = __builtin_bit_cast(f32x4, tv[i]);
;                 *(LAS u32x2_t*)(vw + (c_ >> 2) * 4096 + (key >> 4) * 1024 + (key & 15) * 64 + (c_ & 3) * 16 + (q16_ & 1) * 8) = (u32x2_t){pk2(f_[0], f_[1]), pk2(f_[2], f_[3])}; }
.LBB0_417:
	v_sub_f32_e32 v2, v68, v227
	v_exp_f32_e32 v218, v2
	v_sub_f32_e32 v2, v52, v227
	v_exp_f32_e32 v238, v2
	v_sub_f32_e32 v2, v69, v227
	v_exp_f32_e32 v52, v2
	v_sub_f32_e32 v2, v53, v227
	v_exp_f32_e32 v2, v2
	v_add_f32_e32 v53, v218, v238
	v_sub_f32_e32 v54, v54, v227
	v_exp_f32_e32 v239, v54
	v_add_f32_e32 v68, v52, v2
	v_add_f32_e32 v69, v53, v3
	v_sub_f32_e32 v53, v70, v227
	v_add_f32_e32 v228, v68, v68
	v_add_f32_e32 v229, v68, v69
	v_exp_f32_e32 v53, v53
	v_sub_f32_e32 v54, v71, v227
	v_sub_f32_e32 v55, v55, v227
	v_exp_f32_e32 v54, v54
	v_exp_f32_e32 v228, v55
	v_add_f32_e32 v55, v53, v239
	v_sub_f32_e32 v56, v56, v227
	v_sub_f32_e32 v57, v57, v227
	v_add_f32_e32 v68, v54, v228
	v_add_f32_e32 v69, v55, v229
	v_sub_f32_e32 v55, v72, v227
	v_add_f32_e32 v230, v68, v68
	v_add_f32_e32 v231, v68, v69
	v_exp_f32_e32 v55, v55
	v_exp_f32_e32 v229, v56
	v_sub_f32_e32 v56, v73, v227
	v_exp_f32_e32 v56, v56
	v_exp_f32_e32 v230, v57
	v_add_f32_e32 v57, v55, v229
	v_sub_f32_e32 v58, v58, v227
	v_sub_f32_e32 v59, v59, v227
	v_add_f32_e32 v68, v56, v230
	v_add_f32_e32 v69, v57, v231
	v_sub_f32_e32 v57, v74, v227
	v_add_f32_e32 v72, v68, v68
	v_add_f32_e32 v73, v68, v69
	v_exp_f32_e32 v57, v57
	v_exp_f32_e32 v231, v58
	v_sub_f32_e32 v58, v75, v227
	v_exp_f32_e32 v58, v58
	v_exp_f32_e32 v72, v59
	v_add_f32_e32 v59, v57, v231
	v_cvt_pk_bf16_f32 v53, v53, v54
	v_cvt_pk_bf16_f32 v54, v55, v56
	v_add_f32_e32 v68, v58, v72
	v_add_f32_e32 v69, v59, v73
	v_sub_f32_e32 v59, v76, v227
	v_exp_f32_e32 v70, v59
	v_sub_f32_e32 v59, v60, v227
	v_exp_f32_e32 v73, v59
	v_sub_f32_e32 v59, v77, v227
	v_add_f32_e32 v74, v68, v68
	v_add_f32_e32 v75, v68, v69
	v_exp_f32_e32 v60, v59
	v_sub_f32_e32 v59, v61, v227
	v_exp_f32_e32 v74, v59
	v_add_f32_e32 v61, v70, v73
	v_sub_f32_e32 v59, v78, v227
	v_cvt_pk_bf16_f32 v55, v57, v58
	v_add_f32_e32 v68, v60, v74
	v_add_f32_e32 v69, v61, v75
	v_exp_f32_e32 v61, v59
	v_sub_f32_e32 v59, v62, v227
	v_exp_f32_e32 v240, v59
	v_sub_f32_e32 v59, v79, v227
	v_add_f32_e32 v76, v68, v68
	v_add_f32_e32 v77, v68, v69
	v_exp_f32_e32 v62, v59
	v_sub_f32_e32 v59, v63, v227
	v_exp_f32_e32 v76, v59
	v_add_f32_e32 v63, v61, v240
	v_sub_f32_e32 v59, v80, v227
	v_add3_u32 v58, s73, v215, v221
	v_add_f32_e32 v68, v62, v76
	v_add_f32_e32 v69, v63, v77
	v_exp_f32_e32 v63, v59
	v_sub_f32_e32 v59, v64, v227
	v_exp_f32_e32 v77, v59
	v_sub_f32_e32 v59, v81, v227
	v_add_f32_e32 v78, v68, v68
	v_add_f32_e32 v79, v68, v69
	v_exp_f32_e32 v64, v59
	v_sub_f32_e32 v59, v65, v227
	v_exp_f32_e32 v78, v59
	v_add_f32_e32 v65, v63, v77
	v_sub_f32_e32 v59, v82, v227
	s_waitcnt vmcnt(15)
	v_cvt_pk_bf16_f32 v56, v136, v137
	v_add_f32_e32 v68, v64, v78
	v_add_f32_e32 v69, v65, v79
	v_exp_f32_e32 v79, v59
	v_sub_f32_e32 v59, v66, v227
	v_add3_u32 v66, v58, v219, v220
	v_add_f32_e32 v80, v68, v68
	v_add_f32_e32 v81, v68, v69
	v_exp_f32_e32 v241, v59
	v_cvt_pk_bf16_f32 v57, v138, v139
	s_waitcnt vmcnt(14)
	v_cvt_pk_bf16_f32 v58, v132, v133
	v_cvt_pk_bf16_f32 v59, v134, v135
	v_add_u32_e32 v68, 0x8000, v66
	ds_write2_b64 v68, v[56:57], v[58:59] offset1:32
	s_waitcnt vmcnt(13)
	v_cvt_pk_bf16_f32 v56, v144, v145
	v_cvt_pk_bf16_f32 v57, v146, v147
	s_waitcnt vmcnt(12)
	v_cvt_pk_bf16_f32 v58, v140, v141
	v_cvt_pk_bf16_f32 v59, v142, v143
	ds_write2_b64 v68, v[56:57], v[58:59] offset0:64 offset1:96
	s_waitcnt vmcnt(11)
	v_cvt_pk_bf16_f32 v56, v152, v153
	v_cvt_pk_bf16_f32 v57, v154, v155
	s_waitcnt vmcnt(10)
	v_cvt_pk_bf16_f32 v58, v148, v149
	v_cvt_pk_bf16_f32 v59, v150, v151
	ds_write2_b64 v68, v[56:57], v[58:59] offset0:128 offset1:160
	s_waitcnt vmcnt(9)
; #define LAS __attribute__((address_space(3)))
; __device__ __forceinline__ unsigned pk2(float lo, float hi) { f32x2_t v = {lo, hi}; bf16x2_t b = __builtin_convertvector(v, bf16x2_t); return __builtin_bit_cast(unsigned, b); }
; __device__ __forceinline__ s16x4 vtr(const LAS unsigned char* p) { return __builtin_bit_cast(s16x4, __builtin_amdgcn_ds_read_tr16_b64_v4i16((LAS v4i16_t*)p)); }
; template <int KIND>
; __device__ __forceinline__ void sample_unit(const AttnCtx& C, int u, LAS unsigned char* lds) {
;     ...
;         if (!hasv) {
;             LAS unsigned char* vw = lds + bufi * SBUF + 32768 + j * 8192;
;             const int q16_ = lane & 15, c_ = q16_ >> 1;
; #pragma unroll
;             for (int i = 0; i < 16; ++i) { const int key = 4 * i + (lane >> 4); const f32x4 f_ = __builtin_bit_cast(f32x4, tv[i]);
;                 *(LAS u32x2_t*)(vw + (c_ >> 2) * 4096 + (key >> 4) * 1024 + (key & 15) * 64 + (c_ & 3) * 16 + (q16_ & 1) * 8) = (u32x2_t){pk2(f_[0], f_[1]), pk2(f_[2], f_[3])}; }
;             asm volatile("s_waitcnt lgkmcnt(0)" ::: "memory");
;         }
;         const LAS unsigned char* vp = vt + ((lane >> 4) & 1) * 32 + (lane & 3) * 8 + (4 * hi + ((lane & 15) >> 2)) * 64;
; #pragma unroll
;         for (int d = 0; d < NDB; ++d)
; #pragma unroll
;             for (int ks = 0; ks < 4; ++ks) {
;                 const s16x4 lo = vtr(vp + d * 4096 + ks * 1024), hh = vtr(vp + d * 4096 + ks * 1024 + 512);
;                 const bf16x8 vf = (bf16x8){lo[0], lo[1], lo[2], lo[3], hh[0], hh[1], hh[2], hh[3]};
;                 o[d] = __builtin_amdgcn_mfma_f32_32x32x16_bf16(__builtin_bit_cast(bf16x8, pw[ks]), vf, o[d], 0, 0, 0);
;             }
	v_cvt_pk_bf16_f32 v56, v160, v161
	v_cvt_pk_bf16_f32 v57, v162, v163
	s_waitcnt vmcnt(8)
	v_cvt_pk_bf16_f32 v58, v156, v157
	v_cvt_pk_bf16_f32 v59, v158, v159
	ds_write2_b64 v68, v[56:57], v[58:59] offset0:192 offset1:224
	s_waitcnt vmcnt(7)
	v_cvt_pk_bf16_f32 v56, v168, v169
	v_cvt_pk_bf16_f32 v57, v170, v171
	s_waitcnt vmcnt(6)
	v_cvt_pk_bf16_f32 v58, v164, v165
	v_cvt_pk_bf16_f32 v59, v166, v167
	v_add_u32_e32 v66, 0x8800, v66
	ds_write2_b64 v66, v[56:57], v[58:59] offset1:32
	s_waitcnt vmcnt(5)
	v_cvt_pk_bf16_f32 v56, v176, v177
	v_cvt_pk_bf16_f32 v57, v178, v179
	s_waitcnt vmcnt(4)
	v_cvt_pk_bf16_f32 v58, v172, v173
	v_cvt_pk_bf16_f32 v59, v174, v175
	ds_write2_b64 v66, v[56:57], v[58:59] offset0:64 offset1:96
	s_waitcnt vmcnt(3)
	v_cvt_pk_bf16_f32 v56, v184, v185
	v_cvt_pk_bf16_f32 v57, v186, v187
	s_waitcnt vmcnt(2)
	v_cvt_pk_bf16_f32 v58, v180, v181
	v_cvt_pk_bf16_f32 v59, v182, v183
	ds_write2_b64 v66, v[56:57], v[58:59] offset0:128 offset1:160
	s_waitcnt vmcnt(1)
	v_cvt_pk_bf16_f32 v56, v192, v193
	v_cvt_pk_bf16_f32 v57, v194, v195
	s_waitcnt vmcnt(0)
	v_cvt_pk_bf16_f32 v58, v188, v189
	v_cvt_pk_bf16_f32 v59, v190, v191
	ds_write2_b64 v66, v[56:57], v[58:59] offset0:192 offset1:224
	v_add3_u32 v56, s73, v222, v223
	v_sub_f32_e32 v65, v83, v227
	s_waitcnt lgkmcnt(0)
	v_add3_u32 v83, v56, v224, v225
	v_cvt_pk_bf16_f32 v52, v218, v52
	ds_read_b64_tr_b16 v[56:57], v83 offset:32768
	ds_read_b64_tr_b16 v[58:59], v83 offset:33280
	v_exp_f32_e32 v82, v65
	s_waitcnt lgkmcnt(0)
	v_mfma_f32_32x32x16_bf16 v[36:51], v[52:55], v[56:59], v[36:51]
	v_cvt_pk_bf16_f32 v60, v70, v60
	ds_read_b64_tr_b16 v[68:69], v83 offset:33792
	ds_read_b64_tr_b16 v[70:71], v83 offset:34304
	v_cvt_pk_bf16_f32 v61, v61, v62
	v_cvt_pk_bf16_f32 v62, v63, v64
	v_cvt_pk_bf16_f32 v63, v79, v82
	v_sub_f32_e32 v75, v67, v227
	v_cvt_pk_bf16_f32 v56, v238, v2
	s_waitcnt lgkmcnt(0)
	v_mfma_f32_32x32x16_bf16 v[36:51], v[60:63], v[68:71], v[36:51]
	v_cvt_pk_bf16_f32 v57, v239, v228
	v_cvt_pk_bf16_f32 v58, v229, v230
	v_cvt_pk_bf16_f32 v59, v231, v72
	ds_read_b64_tr_b16 v[64:65], v83 offset:34816
	ds_read_b64_tr_b16 v[66:67], v83 offset:35328
	v_exp_f32_e32 v80, v75
	v_cvt_pk_bf16_f32 v68, v73, v74
	ds_read_b64_tr_b16 v[72:73], v83 offset:35840
	ds_read_b64_tr_b16 v[74:75], v83 offset:36352
	s_waitcnt lgkmcnt(2)
	v_mfma_f32_32x32x16_bf16 v[36:51], v[56:59], v[64:67], v[36:51]
	v_cvt_pk_bf16_f32 v69, v240, v76
	v_cvt_pk_bf16_f32 v70, v77, v78
	v_cvt_pk_bf16_f32 v71, v241, v80
	s_waitcnt lgkmcnt(0)
	s_nop 0
	v_mfma_f32_32x32x16_bf16 v[36:51], v[68:71], v[72:75], v[36:51]
	ds_read_b64_tr_b16 v[64:65], v83 offset:36864
	ds_read_b64_tr_b16 v[66:67], v83 offset:37376
	ds_read_b64_tr_b16 v[72:73], v83 offset:37888
	ds_read_b64_tr_b16 v[74:75], v83 offset:38400
	s_waitcnt lgkmcnt(2)
	v_mfma_f32_32x32x16_bf16 v[18:33], v[52:55], v[64:67], v[18:33]
	s_waitcnt lgkmcnt(0)
	v_mfma_f32_32x32x16_bf16 v[18:33], v[60:63], v[72:75], v[18:33]
	ds_read_b64_tr_b16 v[52:53], v83 offset:38912
	ds_read_b64_tr_b16 v[54:55], v83 offset:39424
	ds_read_b64_tr_b16 v[60:61], v83 offset:39936
	ds_read_b64_tr_b16 v[62:63], v83 offset:40448
	v_add_f32_e32 v83, v79, v241
	s_waitcnt lgkmcnt(2)
	v_mfma_f32_32x32x16_bf16 v[18:33], v[56:59], v[52:55], v[18:33]
	v_add_f32_e64 v52, v82, v80
	v_add_f32_e64 v53, v83, v81
	v_add_f32_e32 v2, v52, v53
	v_add_f32_e32 v210, v210, v2
	s_waitcnt lgkmcnt(0)
	v_mfma_f32_32x32x16_bf16 v[18:33], v[68:71], v[60:63], v[18:33]
	s_cmp_eq_u32 s82, 0xff880000
	s_cbranch_scc1 .LBB0_424

; #define LAS __attribute__((address_space(3)))
; template <int KIND>
; __device__ __forceinline__ void sample_unit(const AttnCtx& C, int u, LAS unsigned char* lds) {
;     ...
;     if (kp == 0) {
; #pragma unroll
;         for (int k = 0; k < TPS - 1; ++k) {
;             const LAS float* ps = (const LAS float*)(lds + (size_t)(grp * (TPS - 1) + k) * PST);
;             const float mb = ps[NDB * 16 * 64 + lane], lb = ps[NDB * 16 * 64 + 64 + lane];
;             const float mt = fmaxf(m_run, mb); const float wa = __builtin_amdgcn_exp2f(m_run - mt), wb = __builtin_amdgcn_exp2f(mb - mt);
;             l_run = l_run * wa + lb * wb; m_run = mt;
;             if (hi == 0) { wsf[r32] = wa; wsf[32 + r32] = wb; }
; #pragma unroll
;             for (int gq = 0; gq < 4; ++gq) { const f32x4 a = *(const LAS f32x4*)(wsf + 8 * gq + 4 * hi), bq = *(const LAS f32x4*)(wsf + 32 + 8 * gq + 4 * hi);
; #pragma unroll
;                 for (int d = 0; d < NDB; ++d)
; #pragma unroll
;                     for (int e = 0; e < 4; ++e) { const int r = 4 * gq + e; o[d][r] = o[d][r] * a[e] + ps[(d * 16 + r) * 64 + lane] * bq[e]; } }
;         }
;         const float lt = l_run + __shfl_xor(l_run, 32);
;         if (hi == 0) wsf[r32] = 1.0f / lt;
;     }
.LBB0_437:
	s_or_b64 exec, exec, s[6:7]
	v_pk_mul_f32 v[230:231], v[128:129], v[230:231]
	v_pk_mul_f32 v[128:129], v[128:129], v[228:229]
	v_pk_fma_f32 v[36:37], v[36:37], v[124:125], v[230:231]
	v_pk_fma_f32 v[18:19], v[18:19], v[124:125], v[128:129]
	v_pk_mul_f32 v[124:125], v[130:131], v[224:225]
	s_waitcnt lgkmcnt(0)
	v_mul_f32_e32 v1, v74, v144
	v_pk_fma_f32 v[20:21], v[20:21], v[126:127], v[124:125]
	v_pk_mul_f32 v[124:125], v[104:105], v[202:203]
	v_pk_mul_f32 v[104:105], v[104:105], v[172:173]
	v_pk_fma_f32 v[40:41], v[40:41], v[84:85], v[124:125]
	v_pk_fma_f32 v[22:23], v[22:23], v[84:85], v[104:105]
	v_pk_mul_f32 v[84:85], v[106:107], v[164:165]
	v_mul_f32_e32 v2, v75, v145
	v_pk_fma_f32 v[24:25], v[24:25], v[86:87], v[84:85]
	v_pk_mul_f32 v[84:85], v[112:113], v[208:209]
	v_fmac_f32_e32 v1, v50, v66
	v_pk_fma_f32 v[44:45], v[44:45], v[88:89], v[84:85]
	v_pk_mul_f32 v[84:85], v[114:115], v[188:189]
	v_fmac_f32_e32 v2, v51, v67
	v_pk_fma_f32 v[46:47], v[46:47], v[90:91], v[84:85]
	v_pk_mul_f32 v[84:85], v[112:113], v[196:197]
	v_pk_mul_f32 v[50:51], v[72:73], v[148:149]
	v_pk_fma_f32 v[26:27], v[26:27], v[88:89], v[84:85]
	v_pk_mul_f32 v[84:85], v[114:115], v[182:183]
	v_pk_fma_f32 v[30:31], v[30:31], v[64:65], v[50:51]
	v_pk_fma_f32 v[28:29], v[28:29], v[90:91], v[84:85]
	v_pk_mul_f32 v[84:85], v[72:73], v[154:155]
	v_pk_mul_f32 v[226:227], v[130:131], v[226:227]
	v_pk_fma_f32 v[48:49], v[48:49], v[64:65], v[84:85]
	v_mul_f32_e32 v64, v74, v136
	v_mul_f32_e32 v65, v75, v137
	v_fmac_f32_e32 v64, v32, v66
	v_fmac_f32_e32 v65, v33, v67
	v_pk_mul_f32 v[32:33], v[100:101], v[200:201]
	v_pk_fma_f32 v[38:39], v[38:39], v[126:127], v[226:227]
	v_pk_fma_f32 v[32:33], v[36:37], v[96:97], v[32:33]
	v_pk_mul_f32 v[36:37], v[102:103], v[180:181]
	v_pk_mul_f32 v[124:125], v[106:107], v[184:185]
	v_pk_fma_f32 v[38:39], v[38:39], v[98:99], v[36:37]
	v_pk_mul_f32 v[36:37], v[100:101], v[186:187]
	v_pk_fma_f32 v[42:43], v[42:43], v[86:87], v[124:125]
	v_pk_fma_f32 v[18:19], v[18:19], v[96:97], v[36:37]
	v_pk_mul_f32 v[36:37], v[102:103], v[168:169]
	v_pk_mul_f32 v[50:51], v[76:77], v[146:147]
	v_pk_fma_f32 v[20:21], v[20:21], v[98:99], v[36:37]
	v_pk_mul_f32 v[36:37], v[92:93], v[158:159]
	v_mov_b32_e32 v90, v55
	v_pk_fma_f32 v[40:41], v[40:41], v[56:57], v[36:37]
	v_pk_mul_f32 v[36:37], v[94:95], v[152:153]
	v_mov_b32_e32 v91, v63
	v_pk_fma_f32 v[42:43], v[42:43], v[58:59], v[36:37]
	v_pk_mul_f32 v[36:37], v[92:93], v[156:157]
	v_pk_fma_f32 v[30:31], v[30:31], v[68:69], v[50:51]
	v_pk_fma_f32 v[22:23], v[22:23], v[56:57], v[36:37]
	v_pk_mul_f32 v[36:37], v[94:95], v[150:151]
	v_mul_f32_e32 v56, v79, v139
	v_pk_fma_f32 v[24:25], v[24:25], v[58:59], v[36:37]
	v_pk_mul_f32 v[36:37], v[108:109], v[178:179]
	v_fmac_f32_e32 v56, v65, v71
	v_pk_fma_f32 v[44:45], v[44:45], v[80:81], v[36:37]
	v_pk_mul_f32 v[36:37], v[110:111], v[160:161]
	v_pk_mul_f32 v[50:51], v[120:121], v[220:221]
	v_pk_fma_f32 v[46:47], v[46:47], v[82:83], v[36:37]
	v_pk_mul_f32 v[36:37], v[108:109], v[170:171]
	v_mov_b32_e32 v57, v17
	v_pk_fma_f32 v[26:27], v[26:27], v[80:81], v[36:37]
	v_pk_mul_f32 v[36:37], v[110:111], v[162:163]
	v_pk_mul_f32 v[58:59], v[122:123], v[206:207]
	v_pk_fma_f32 v[28:29], v[28:29], v[82:83], v[36:37]
	v_pk_mul_f32 v[36:37], v[76:77], v[142:143]
	v_pk_mul_f32 v[66:67], v[122:123], v[204:205]
	v_pk_fma_f32 v[48:49], v[48:49], v[68:69], v[36:37]
	v_mul_f32_e32 v37, v78, v140
	v_fmac_f32_e32 v37, v1, v70
	v_mul_f32_e32 v36, v79, v141
	v_fmac_f32_e32 v36, v2, v71
	v_mul_f32_e32 v1, v78, v138
	v_mul_f32_e32 v86, v37, v54
	v_mov_b32_e32 v37, v193
	v_fmac_f32_e32 v1, v64, v70
	v_pk_mul_f32 v[36:37], v[36:37], v[90:91]
	v_pk_mul_f32 v[64:65], v[120:121], v[214:215]
	v_mov_b32_e32 v87, v36
	v_mov_b32_e32 v89, v37
	v_pk_fma_f32 v[36:37], v[32:33], v[8:9], v[50:51]
	v_pk_mul_f32 v[32:33], v[60:61], v[34:35]
	v_mul_f32_e32 v34, v1, v54
	v_pk_mul_f32 v[54:55], v[56:57], v[90:91]
	v_pk_mul_f32 v[68:69], v[116:117], v[190:191]
	v_pk_mul_f32 v[70:71], v[118:119], v[166:167]
	v_pk_mul_f32 v[72:73], v[116:117], v[176:177]
	v_pk_mul_f32 v[74:75], v[118:119], v[174:175]
	v_pk_mul_f32 v[76:77], v[132:133], v[222:223]
	v_pk_mul_f32 v[78:79], v[134:135], v[212:213]
	v_pk_mul_f32 v[80:81], v[132:133], v[218:219]
	v_pk_mul_f32 v[82:83], v[134:135], v[210:211]
	v_pk_mul_f32 v[84:85], v[60:61], v[194:195]
	v_mul_f32_e32 v88, v62, v192
	v_mul_f32_e32 v16, v62, v16
	v_mov_b32_e32 v35, v54
	v_mov_b32_e32 v17, v55
	v_pk_fma_f32 v[38:39], v[38:39], v[10:11], v[58:59]
	v_pk_fma_f32 v[40:41], v[40:41], v[4:5], v[68:69]
	v_pk_fma_f32 v[42:43], v[42:43], v[6:7], v[70:71]
	v_pk_fma_f32 v[44:45], v[44:45], v[12:13], v[76:77]
	v_pk_fma_f32 v[46:47], v[46:47], v[14:15], v[78:79]
	v_pk_fma_f32 v[48:49], v[48:49], v[52:53], v[84:85]
	v_add_f32_e32 v50, v86, v88
	v_add_f32_e32 v51, v87, v89
	v_pk_fma_f32 v[18:19], v[18:19], v[8:9], v[64:65]
	v_pk_fma_f32 v[20:21], v[20:21], v[10:11], v[66:67]
	v_pk_fma_f32 v[22:23], v[22:23], v[4:5], v[72:73]
	v_pk_fma_f32 v[24:25], v[24:25], v[6:7], v[74:75]
	v_pk_fma_f32 v[26:27], v[26:27], v[12:13], v[80:81]
	v_pk_fma_f32 v[28:29], v[28:29], v[14:15], v[82:83]
	v_pk_fma_f32 v[30:31], v[30:31], v[52:53], v[32:33]
	v_add_f32_e32 v32, v34, v16
	v_add_f32_e32 v33, v35, v17

; template <int KIND>
; __device__ __forceinline__ void sample_unit(const AttnCtx& C, int u, LAS unsigned char* lds) {
;     ...
;         if (wid == 0) {
;             float loc[4]; float run = 0.f;
; #pragma unroll
;             for (int j = 0; j < 4; ++j) { const int c = 63 - (4 * lane + j); const float v = (c >= 0) ? tot[c] : 0.f; run += v; loc[j] = run; }
;             float incl = run;
; #pragma unroll
;             for (int o = 1; o < 64; o <<= 1) { const float t = __shfl_up(incl, o); if (lane >= o) incl += t; }
;             const float excl = incl - run;
; #pragma unroll
;             for (int j = 0; j < 4; ++j) { const int c = 63 - (4 * lane + j); if (c >= 0) dd[c] = -(excl + loc[j]); }
;             if (lane == 0) dd[64] = 0.f;
.LBB0_735:
	s_or_b64 exec, exec, s[2:3]
	s_and_saveexec_b64 s[2:3], vcc
	v_or_b32_e32 v2, 1, v1
	v_sub_u32_e32 v2, 63, v2
	v_lshl_add_u32 v2, v2, 2, 0
	v_add_u32_e32 v2, 0x22400, v2
	ds_read_b32 v4, v2
	s_or_b64 exec, exec, s[2:3]
	v_mov_b32_e32 v6, 0
	v_mov_b32_e32 v7, 0
	s_and_saveexec_b64 s[2:3], vcc
	v_or_b32_e32 v2, 2, v1
	v_sub_u32_e32 v2, 63, v2
	v_lshl_add_u32 v2, v2, 2, 0
	v_add_u32_e32 v2, 0x22400, v2
	ds_read_b32 v7, v2
	s_or_b64 exec, exec, s[2:3]
	v_or_b32_e32 v2, 3, v1
	v_sub_u32_e32 v2, 63, v2
	v_lshl_add_u32 v2, v2, 2, 0
	s_and_saveexec_b64 s[2:3], vcc
	v_add_u32_e32 v6, 0x22400, v2
	ds_read_b32 v6, v6
	s_or_b64 exec, exec, s[2:3]
	v_and_b32_e32 v9, 64, v230
	v_add_u32_e32 v8, -1, v230
	s_waitcnt lgkmcnt(0)
	v_add_f32_e32 v4, v5, v4
	v_cmp_lt_i32_e64 s[2:3], v8, v9
	v_add_f32_e32 v7, v4, v7
	v_add_f32_e32 v6, v7, v6
	v_cndmask_b32_e64 v8, v8, v230, s[2:3]
	v_lshlrev_b32_e32 v8, 2, v8
	ds_bpermute_b32 v8, v8, v6
	v_add_u32_e32 v10, -2, v230
	v_cmp_lt_i32_e64 s[4:5], v10, v9
	v_cmp_eq_u32_e64 s[2:3], 0, v35
	s_waitcnt lgkmcnt(0)
	v_add_f32_e32 v8, v6, v8
	v_cndmask_b32_e64 v10, v10, v230, s[4:5]
	v_cndmask_b32_e64 v8, v8, v6, s[2:3]
	v_lshlrev_b32_e32 v10, 2, v10
	ds_bpermute_b32 v10, v10, v8
	v_cmp_gt_u32_e64 s[4:5], 2, v35
	s_waitcnt lgkmcnt(0)
	v_add_f32_e32 v10, v8, v10
	v_cndmask_b32_e64 v8, v10, v8, s[4:5]
	v_add_u32_e32 v10, -4, v230
	v_cmp_lt_i32_e64 s[4:5], v10, v9
	s_nop 1
	v_cndmask_b32_e64 v10, v10, v230, s[4:5]
	v_lshlrev_b32_e32 v10, 2, v10
	ds_bpermute_b32 v10, v10, v8
	v_cmp_gt_u32_e64 s[4:5], 4, v35
	s_waitcnt lgkmcnt(0)
	v_add_f32_e32 v10, v8, v10
	v_cndmask_b32_e64 v8, v10, v8, s[4:5]
	v_add_u32_e32 v10, -8, v230
	v_cmp_lt_i32_e64 s[4:5], v10, v9
	s_nop 1
	v_cndmask_b32_e64 v9, v10, v230, s[4:5]
	v_lshlrev_b32_e32 v9, 2, v9
	ds_bpermute_b32 v9, v9, v8
	s_and_saveexec_b64 s[4:5], vcc
	s_cbranch_execz .LBB0_743
	s_waitcnt lgkmcnt(0)
	v_add_f32_e32 v9, v8, v9
	v_cmp_gt_u32_e32 vcc, 8, v35
	v_add_u32_e32 v2, 0x22580, v2
	s_nop 0
	v_cndmask_b32_e32 v8, v9, v8, vcc
	v_sub_f32_e32 v10, v8, v6
	v_add_f32_e32 v4, v4, v10
	v_add_f32_e32 v5, v5, v10
	s_nop 0
	v_xor_b32_e32 v9, 0x80000000, v5
	v_xor_b32_e32 v8, 0x80000000, v4
	v_add_f32_e32 v4, v6, v10
	v_add_f32_e32 v5, v7, v10
	s_nop 0
	v_xor_b32_e32 v7, 0x80000000, v5
	v_xor_b32_e32 v6, 0x80000000, v4
	ds_write_b128 v2, v[6:9]

; #define LAS __attribute__((address_space(3)))
; __device__ __forceinline__ unsigned pk2(float lo, float hi) { f32x2_t v = {lo, hi}; bf16x2_t b = __builtin_convertvector(v, bf16x2_t); return __builtin_bit_cast(unsigned, b); }
; __device__ __forceinline__ s16x4 vtr(const LAS unsigned char* p) { return __builtin_bit_cast(s16x4, __builtin_amdgcn_ds_read_tr16_b64_v4i16((LAS v4i16_t*)p)); }
; template <int KIND>
; __device__ __forceinline__ void sample_unit(const AttnCtx& C, int u, LAS unsigned char* lds) {
;     ...
;         float rs = 0.f;
; #pragma unroll
;         for (int r = 0; r < 16; ++r) { p0[r] = __builtin_amdgcn_exp2f(p0[r] - m_run); p1[r] = __builtin_amdgcn_exp2f(p1[r] - m_run); rs += p0[r] + p1[r]; }
;         l_run += rs;
;         v4u pw[4];
;         pw[0] = (v4u){pk2(p0[0], p0[1]), pk2(p0[2], p0[3]), pk2(p0[4], p0[5]), pk2(p0[6], p0[7])};
;         pw[1] = (v4u){pk2(p0[8], p0[9]), pk2(p0[10], p0[11]), pk2(p0[12], p0[13]), pk2(p0[14], p0[15])};
;         pw[2] = (v4u){pk2(p1[0], p1[1]), pk2(p1[2], p1[3]), pk2(p1[4], p1[5]), pk2(p1[6], p1[7])};
;         pw[3] = (v4u){pk2(p1[8], p1[9]), pk2(p1[10], p1[11]), pk2(p1[12], p1[13]), pk2(p1[14], p1[15])};
;         if (!hasv) {
;             LAS unsigned char* vw = lds + bufi * SBUF + 32768 + j * 8192;
;             const int q16_ = lane & 15, c_ = q16_ >> 1;
; #pragma unroll
;             for (int i = 0; i < 16; ++i) { const int key = 4 * i + (lane >> 4); const f32x4 f_ = __builtin_bit_cast(f32x4, tv[i]);
;                 *(LAS u32x2_t*)(vw + (c_ >> 2) * 4096 + (key >> 4) * 1024 + (key & 15) * 64 + (c_ & 3) * 16 + (q16_ & 1) * 8) = (u32x2_t){pk2(f_[0], f_[1]), pk2(f_[2], f_[3])}; }
;             asm volatile("s_waitcnt lgkmcnt(0)" ::: "memory");
;         }
;         const LAS unsigned char* vp = vt + ((lane >> 4) & 1) * 32 + (lane & 3) * 8 + (4 * hi + ((lane & 15) >> 2)) * 64;
; #pragma unroll
;         for (int d = 0; d < NDB; ++d)
; #pragma unroll
;             for (int ks = 0; ks < 4; ++ks) {
;                 const s16x4 lo = vtr(vp + d * 4096 + ks * 1024), hh = vtr(vp + d * 4096 + ks * 1024 + 512);
;                 const bf16x8 vf = (bf16x8){lo[0], lo[1], lo[2], lo[3], hh[0], hh[1], hh[2], hh[3]};
;                 o[d] = __builtin_amdgcn_mfma_f32_32x32x16_bf16(__builtin_bit_cast(bf16x8, pw[ks]), vf, o[d], 0, 0, 0);
;             }
.LBB0_759:
	v_sub_f32_e32 v15, v114, v223
	v_exp_f32_e32 v50, v15
	v_sub_f32_e32 v15, v115, v223
	v_sub_f32_e32 v2, v2, v223
	v_exp_f32_e32 v129, v15
	v_exp_f32_e32 v16, v2
	v_sub_f32_e32 v2, v113, v223
	v_exp_f32_e32 v2, v2
	v_add_f32_e32 v17, v50, v129
	v_sub_f32_e32 v15, v111, v223
	v_sub_f32_e32 v13, v13, v223
	v_add_f32_e32 v44, v16, v2
	v_add_f32_e32 v45, v17, v3
	v_exp_f32_e32 v17, v15
	v_sub_f32_e32 v15, v112, v223
	v_exp_f32_e32 v130, v15
	v_sub_f32_e32 v15, v109, v223
	v_add_f32_e32 v114, v44, v44
	v_add_f32_e32 v115, v44, v45
	v_exp_f32_e32 v44, v15
	v_sub_f32_e32 v15, v110, v223
	v_exp_f32_e32 v114, v15
	v_add_f32_e32 v45, v17, v130
	v_sub_f32_e32 v15, v107, v223
	v_exp_f32_e32 v118, v13
	v_add_f32_e32 v46, v44, v114
	v_add_f32_e32 v47, v45, v115
	v_exp_f32_e32 v45, v15
	v_sub_f32_e32 v15, v108, v223
	v_exp_f32_e32 v115, v15
	v_sub_f32_e32 v15, v105, v223
	v_add_f32_e32 v110, v46, v46
	v_add_f32_e32 v111, v46, v47
	v_exp_f32_e32 v46, v15
	v_sub_f32_e32 v15, v106, v223
	v_exp_f32_e32 v110, v15
	v_add_f32_e32 v47, v45, v115
	v_sub_f32_e32 v15, v103, v223
	v_sub_f32_e32 v13, v14, v223
	v_add_f32_e32 v48, v46, v110
	v_add_f32_e32 v49, v47, v111
	v_exp_f32_e32 v47, v15
	v_sub_f32_e32 v15, v104, v223
	v_exp_f32_e32 v103, v15
	v_sub_f32_e32 v15, v42, v223
	v_add_f32_e32 v108, v48, v48
	v_add_f32_e32 v109, v48, v49
	v_exp_f32_e32 v42, v15
	v_sub_f32_e32 v15, v43, v223
	v_exp_f32_e32 v108, v15
	v_add_f32_e32 v43, v47, v103
	v_sub_f32_e32 v15, v40, v223
	v_sub_f32_e32 v11, v11, v223
	v_add_f32_e32 v48, v42, v108
	v_add_f32_e32 v49, v43, v109
	v_exp_f32_e32 v43, v15
	v_sub_f32_e32 v15, v41, v223
	v_exp_f32_e32 v109, v15
	v_sub_f32_e32 v15, v38, v223
	v_add_f32_e32 v112, v48, v48
	v_add_f32_e32 v113, v48, v49
	v_exp_f32_e32 v38, v15
	v_sub_f32_e32 v15, v39, v223
	v_exp_f32_e32 v112, v15
	v_add_f32_e32 v39, v43, v109
	v_sub_f32_e32 v15, v36, v223
	v_exp_f32_e32 v111, v15
	v_add_f32_e32 v40, v38, v112
	v_add_f32_e32 v41, v39, v113
	v_sub_f32_e32 v15, v37, v223
	v_add_f32_e32 v116, v40, v40
	v_add_f32_e32 v117, v40, v41
	v_exp_f32_e32 v131, v15
	v_exp_f32_e32 v116, v13
	v_exp_f32_e32 v113, v11
	v_sub_f32_e32 v11, v12, v223
	v_add_f32_e32 v119, v111, v131
	v_add_f32_e32 v14, v118, v116
	v_add_f32_e32 v15, v119, v117
	v_sub_f32_e32 v9, v9, v223
	v_add_f32_e32 v120, v14, v14
	v_add_f32_e32 v121, v14, v15
	v_exp_f32_e32 v117, v11
	v_exp_f32_e32 v122, v9
	v_sub_f32_e32 v9, v10, v223
	v_exp_f32_e32 v120, v9
	v_add_f32_e32 v123, v113, v117
	v_lshlrev_b32_e32 v12, 4, v35
	v_sub_f32_e32 v7, v7, v223
	v_add_f32_e32 v10, v122, v120
	v_add_f32_e32 v11, v123, v121
	v_and_b32_e32 v12, 0xc0, v12
	v_add_f32_e32 v126, v10, v10
	v_add_f32_e32 v127, v10, v11
	v_lshlrev_b32_e32 v10, 1, v35
	v_lshlrev_b32_e32 v11, 3, v35
	v_and_b32_e32 v10, 32, v10
	v_and_b32_e32 v11, 24, v11
	v_add3_u32 v10, 0, v10, v11
	v_lshlrev_b32_e32 v11, 8, v132
	v_exp_f32_e32 v119, v7
	v_sub_f32_e32 v7, v8, v223
	v_add3_u32 v123, v10, v11, v12
	v_exp_f32_e32 v121, v7
	v_sub_f32_e32 v14, v6, v223
	v_cvt_pk_bf16_f32 v6, v50, v16
	v_cvt_pk_bf16_f32 v7, v17, v44
	v_cvt_pk_bf16_f32 v8, v45, v46
	v_cvt_pk_bf16_f32 v9, v47, v42
	ds_read_b64_tr_b16 v[10:11], v123 offset:32768
	ds_read_b64_tr_b16 v[12:13], v123 offset:33280
	v_exp_f32_e32 v128, v14
	v_cvt_pk_bf16_f32 v14, v43, v38
	s_waitcnt lgkmcnt(0)
	v_mfma_f32_32x32x16_bf16 v[36:51], v[6:9], v[10:13], v[18:33]
	ds_read_b64_tr_b16 v[104:105], v123 offset:33792
	ds_read_b64_tr_b16 v[106:107], v123 offset:34304
	v_cvt_pk_bf16_f32 v15, v111, v118
	v_cvt_pk_bf16_f32 v16, v113, v122
	v_cvt_pk_bf16_f32 v17, v119, v128
	v_cvt_pk_bf16_f32 v10, v129, v2
	v_cvt_pk_bf16_f32 v11, v130, v114
	v_cvt_pk_bf16_f32 v12, v115, v110
	s_waitcnt lgkmcnt(0)
	v_mfma_f32_32x32x16_bf16 v[36:51], v[14:17], v[104:107], v[36:51]
	v_cvt_pk_bf16_f32 v13, v103, v108
	ds_read_b64_tr_b16 v[104:105], v123 offset:34816
	ds_read_b64_tr_b16 v[106:107], v123 offset:35328
	v_sub_f32_e32 v4, v4, v223
	v_exp_f32_e32 v126, v4
	v_cvt_pk_bf16_f32 v108, v109, v112
	ds_read_b64_tr_b16 v[112:113], v123 offset:35840
	ds_read_b64_tr_b16 v[114:115], v123 offset:36352
	v_cvt_pk_bf16_f32 v109, v131, v116
	s_waitcnt lgkmcnt(2)
	v_mfma_f32_32x32x16_bf16 v[36:51], v[10:13], v[104:107], v[36:51]
	v_cvt_pk_bf16_f32 v110, v117, v120
	v_cvt_pk_bf16_f32 v111, v121, v126
	v_add_f32_e32 v129, v119, v121
	s_waitcnt lgkmcnt(0)
	v_mfma_f32_32x32x16_bf16 v[36:51], v[108:111], v[112:115], v[36:51]
	ds_read_b64_tr_b16 v[104:105], v123 offset:36864
	ds_read_b64_tr_b16 v[106:107], v123 offset:37376
	ds_read_b64_tr_b16 v[112:113], v123 offset:37888
	ds_read_b64_tr_b16 v[114:115], v123 offset:38400
	s_waitcnt lgkmcnt(2)
	v_mfma_f32_32x32x16_bf16 v[18:33], v[6:9], v[104:107], v[18:33]
	s_waitcnt lgkmcnt(0)
	v_mfma_f32_32x32x16_bf16 v[18:33], v[14:17], v[112:115], v[18:33]
	ds_read_b64_tr_b16 v[6:7], v123 offset:38912
	ds_read_b64_tr_b16 v[8:9], v123 offset:39424
	ds_read_b64_tr_b16 v[14:15], v123 offset:39936
	ds_read_b64_tr_b16 v[16:17], v123 offset:40448
	s_waitcnt lgkmcnt(2)
	v_mfma_f32_32x32x16_bf16 v[18:33], v[10:13], v[6:9], v[18:33]
	v_add_f32_e64 v6, v128, v126
	v_add_f32_e64 v7, v129, v127
	v_add_f32_e32 v2, v6, v7
	v_add_f32_e32 v210, v5, v2
	s_waitcnt lgkmcnt(0)
	v_mfma_f32_32x32x16_bf16 v[18:33], v[108:111], v[14:17], v[18:33]

; #define LAS __attribute__((address_space(3)))
; __device__ __forceinline__ unsigned pk2(float lo, float hi) { f32x2_t v = {lo, hi}; bf16x2_t b = __builtin_convertvector(v, bf16x2_t); return __builtin_bit_cast(unsigned, b); }
; template <int KIND>
; __device__ __forceinline__ void sample_unit(const AttnCtx& C, int u, LAS unsigned char* lds) {
;     ...
;         float rs = 0.f;
; #pragma unroll
;         for (int r = 0; r < 16; ++r) { p0[r] = __builtin_amdgcn_exp2f(p0[r] - m_run); p1[r] = __builtin_amdgcn_exp2f(p1[r] - m_run); rs += p0[r] + p1[r]; }
;         l_run += rs;
;         v4u pw[4];
;         pw[0] = (v4u){pk2(p0[0], p0[1]), pk2(p0[2], p0[3]), pk2(p0[4], p0[5]), pk2(p0[6], p0[7])};
;         pw[1] = (v4u){pk2(p0[8], p0[9]), pk2(p0[10], p0[11]), pk2(p0[12], p0[13]), pk2(p0[14], p0[15])};
;         pw[2] = (v4u){pk2(p1[0], p1[1]), pk2(p1[2], p1[3]), pk2(p1[4], p1[5]), pk2(p1[6], p1[7])};
;         pw[3] = (v4u){pk2(p1[8], p1[9]), pk2(p1[10], p1[11]), pk2(p1[12], p1[13]), pk2(p1[14], p1[15])};
;         if (!hasv) {
;             LAS unsigned char* vw = lds + bufi * SBUF + 32768 + j * 8192;
;             const int q16_ = lane & 15, c_ = q16_ >> 1;
; #pragma unroll
;             for (int i = 0; i < 16; ++i) { const int key = 4 * i + (lane >> 4); const f32x4 f_ = __builtin_bit_cast(f32x4, tv[i]);
;                 *(LAS u32x2_t*)(vw + (c_ >> 2) * 4096 + (key >> 4) * 1024 + (key & 15) * 64 + (c_ & 3) * 16 + (q16_ & 1) * 8) = (u32x2_t){pk2(f_[0], f_[1]), pk2(f_[2], f_[3])}; }
.LBB0_774:
	v_sub_f32_e32 v2, v68, v225
	v_exp_f32_e32 v223, v2
	v_sub_f32_e32 v2, v52, v225
	v_exp_f32_e32 v236, v2
	v_sub_f32_e32 v2, v69, v225
	v_exp_f32_e32 v52, v2
	v_sub_f32_e32 v2, v53, v225
	v_exp_f32_e32 v2, v2
	v_add_f32_e32 v53, v223, v236
	v_sub_f32_e32 v54, v54, v225
	v_exp_f32_e32 v237, v54
	v_add_f32_e32 v68, v52, v2
	v_add_f32_e32 v69, v53, v3
	v_sub_f32_e32 v53, v70, v225
	v_add_f32_e32 v226, v68, v68
	v_add_f32_e32 v227, v68, v69
	v_exp_f32_e32 v53, v53
	v_sub_f32_e32 v54, v71, v225
	v_sub_f32_e32 v55, v55, v225
	v_exp_f32_e32 v54, v54
	v_exp_f32_e32 v226, v55
	v_add_f32_e32 v55, v53, v237
	v_sub_f32_e32 v56, v56, v225
	v_sub_f32_e32 v57, v57, v225
	v_add_f32_e32 v68, v54, v226
	v_add_f32_e32 v69, v55, v227
	v_sub_f32_e32 v55, v72, v225
	v_add_f32_e32 v228, v68, v68
	v_add_f32_e32 v229, v68, v69
	v_exp_f32_e32 v55, v55
	v_exp_f32_e32 v227, v56
	v_sub_f32_e32 v56, v73, v225
	v_exp_f32_e32 v56, v56
	v_exp_f32_e32 v228, v57
	v_add_f32_e32 v57, v55, v227
	v_sub_f32_e32 v58, v58, v225
	v_sub_f32_e32 v59, v59, v225
	v_add_f32_e32 v68, v56, v228
	v_add_f32_e32 v69, v57, v229
	v_sub_f32_e32 v57, v74, v225
	v_add_f32_e32 v72, v68, v68
	v_add_f32_e32 v73, v68, v69
	v_exp_f32_e32 v57, v57
	v_exp_f32_e32 v229, v58
	v_sub_f32_e32 v58, v75, v225
	v_exp_f32_e32 v58, v58
	v_exp_f32_e32 v72, v59
	v_add_f32_e32 v59, v57, v229
	v_cvt_pk_bf16_f32 v53, v53, v54
	v_cvt_pk_bf16_f32 v54, v55, v56
	v_add_f32_e32 v68, v58, v72
	v_add_f32_e32 v69, v59, v73
	v_sub_f32_e32 v59, v76, v225
	v_exp_f32_e32 v70, v59
	v_sub_f32_e32 v59, v60, v225
	v_exp_f32_e32 v73, v59
	v_sub_f32_e32 v59, v77, v225
	v_add_f32_e32 v74, v68, v68
	v_add_f32_e32 v75, v68, v69
	v_exp_f32_e32 v60, v59
	v_sub_f32_e32 v59, v61, v225
	v_exp_f32_e32 v74, v59
	v_add_f32_e32 v61, v70, v73
	v_sub_f32_e32 v59, v78, v225
	v_cvt_pk_bf16_f32 v55, v57, v58
	v_add_f32_e32 v68, v60, v74
	v_add_f32_e32 v69, v61, v75
	v_exp_f32_e32 v61, v59
	v_sub_f32_e32 v59, v62, v225
	v_exp_f32_e32 v238, v59
	v_sub_f32_e32 v59, v79, v225
	v_add_f32_e32 v76, v68, v68
	v_add_f32_e32 v77, v68, v69
	v_exp_f32_e32 v62, v59
	v_sub_f32_e32 v59, v63, v225
	v_exp_f32_e32 v76, v59
	v_add_f32_e32 v63, v61, v238
	v_sub_f32_e32 v59, v80, v225
	v_add3_u32 v58, s73, v215, v218
	v_add_f32_e32 v68, v62, v76
	v_add_f32_e32 v69, v63, v77
	v_exp_f32_e32 v63, v59
	v_sub_f32_e32 v59, v64, v225
	v_exp_f32_e32 v77, v59
	v_sub_f32_e32 v59, v81, v225
	v_add_f32_e32 v78, v68, v68
	v_add_f32_e32 v79, v68, v69
	v_exp_f32_e32 v64, v59
	v_sub_f32_e32 v59, v65, v225
	v_exp_f32_e32 v78, v59
	v_add_f32_e32 v65, v63, v77
	v_sub_f32_e32 v59, v82, v225
	s_waitcnt vmcnt(15)
	v_cvt_pk_bf16_f32 v56, v136, v137
	v_add_f32_e32 v68, v64, v78
	v_add_f32_e32 v69, v65, v79
	v_exp_f32_e32 v79, v59
	v_sub_f32_e32 v59, v66, v225
	v_add3_u32 v66, v58, v216, v217
	v_add_f32_e32 v80, v68, v68
	v_add_f32_e32 v81, v68, v69
	v_exp_f32_e32 v239, v59
	v_cvt_pk_bf16_f32 v57, v138, v139
	s_waitcnt vmcnt(14)
	v_cvt_pk_bf16_f32 v58, v132, v133
	v_cvt_pk_bf16_f32 v59, v134, v135
	v_add_u32_e32 v68, 0x8000, v66
	ds_write2_b64 v68, v[56:57], v[58:59] offset1:32
	s_waitcnt vmcnt(13)
	v_cvt_pk_bf16_f32 v56, v144, v145
	v_cvt_pk_bf16_f32 v57, v146, v147
	s_waitcnt vmcnt(12)
	v_cvt_pk_bf16_f32 v58, v140, v141
	v_cvt_pk_bf16_f32 v59, v142, v143
	ds_write2_b64 v68, v[56:57], v[58:59] offset0:64 offset1:96
	s_waitcnt vmcnt(11)
	v_cvt_pk_bf16_f32 v56, v152, v153
	v_cvt_pk_bf16_f32 v57, v154, v155
	s_waitcnt vmcnt(10)
	v_cvt_pk_bf16_f32 v58, v148, v149
	v_cvt_pk_bf16_f32 v59, v150, v151
	ds_write2_b64 v68, v[56:57], v[58:59] offset0:128 offset1:160
	s_waitcnt vmcnt(9)
; #define LAS __attribute__((address_space(3)))
; __device__ __forceinline__ unsigned pk2(float lo, float hi) { f32x2_t v = {lo, hi}; bf16x2_t b = __builtin_convertvector(v, bf16x2_t); return __builtin_bit_cast(unsigned, b); }
; __device__ __forceinline__ s16x4 vtr(const LAS unsigned char* p) { return __builtin_bit_cast(s16x4, __builtin_amdgcn_ds_read_tr16_b64_v4i16((LAS v4i16_t*)p)); }
; template <int KIND>
; __device__ __forceinline__ void sample_unit(const AttnCtx& C, int u, LAS unsigned char* lds) {
;     ...
;         if (!hasv) {
;             LAS unsigned char* vw = lds + bufi * SBUF + 32768 + j * 8192;
;             const int q16_ = lane & 15, c_ = q16_ >> 1;
; #pragma unroll
;             for (int i = 0; i < 16; ++i) { const int key = 4 * i + (lane >> 4); const f32x4 f_ = __builtin_bit_cast(f32x4, tv[i]);
;                 *(LAS u32x2_t*)(vw + (c_ >> 2) * 4096 + (key >> 4) * 1024 + (key & 15) * 64 + (c_ & 3) * 16 + (q16_ & 1) * 8) = (u32x2_t){pk2(f_[0], f_[1]), pk2(f_[2], f_[3])}; }
;             asm volatile("s_waitcnt lgkmcnt(0)" ::: "memory");
;         }
;         const LAS unsigned char* vp = vt + ((lane >> 4) & 1) * 32 + (lane & 3) * 8 + (4 * hi + ((lane & 15) >> 2)) * 64;
; #pragma unroll
;         for (int d = 0; d < NDB; ++d)
; #pragma unroll
;             for (int ks = 0; ks < 4; ++ks) {
;                 const s16x4 lo = vtr(vp + d * 4096 + ks * 1024), hh = vtr(vp + d * 4096 + ks * 1024 + 512);
;                 const bf16x8 vf = (bf16x8){lo[0], lo[1], lo[2], lo[3], hh[0], hh[1], hh[2], hh[3]};
;                 o[d] = __builtin_amdgcn_mfma_f32_32x32x16_bf16(__builtin_bit_cast(bf16x8, pw[ks]), vf, o[d], 0, 0, 0);
;             }
	v_cvt_pk_bf16_f32 v56, v160, v161
	v_cvt_pk_bf16_f32 v57, v162, v163
	s_waitcnt vmcnt(8)
	v_cvt_pk_bf16_f32 v58, v156, v157
	v_cvt_pk_bf16_f32 v59, v158, v159
	ds_write2_b64 v68, v[56:57], v[58:59] offset0:192 offset1:224
	s_waitcnt vmcnt(7)
	v_cvt_pk_bf16_f32 v56, v168, v169
	v_cvt_pk_bf16_f32 v57, v170, v171
	s_waitcnt vmcnt(6)
	v_cvt_pk_bf16_f32 v58, v164, v165
	v_cvt_pk_bf16_f32 v59, v166, v167
	v_add_u32_e32 v66, 0x8800, v66
	ds_write2_b64 v66, v[56:57], v[58:59] offset1:32
	s_waitcnt vmcnt(5)
	v_cvt_pk_bf16_f32 v56, v176, v177
	v_cvt_pk_bf16_f32 v57, v178, v179
	s_waitcnt vmcnt(4)
	v_cvt_pk_bf16_f32 v58, v172, v173
	v_cvt_pk_bf16_f32 v59, v174, v175
	ds_write2_b64 v66, v[56:57], v[58:59] offset0:64 offset1:96
	s_waitcnt vmcnt(3)
	v_cvt_pk_bf16_f32 v56, v184, v185
	v_cvt_pk_bf16_f32 v57, v186, v187
	s_waitcnt vmcnt(2)
	v_cvt_pk_bf16_f32 v58, v180, v181
	v_cvt_pk_bf16_f32 v59, v182, v183
	ds_write2_b64 v66, v[56:57], v[58:59] offset0:128 offset1:160
	s_waitcnt vmcnt(1)
	v_cvt_pk_bf16_f32 v56, v192, v193
	v_cvt_pk_bf16_f32 v57, v194, v195
	s_waitcnt vmcnt(0)
	v_cvt_pk_bf16_f32 v58, v188, v189
	v_cvt_pk_bf16_f32 v59, v190, v191
	ds_write2_b64 v66, v[56:57], v[58:59] offset0:192 offset1:224
	v_add3_u32 v56, s73, v219, v220
	v_sub_f32_e32 v65, v83, v225
	s_waitcnt lgkmcnt(0)
	v_add3_u32 v83, v56, v221, v222
	v_cvt_pk_bf16_f32 v52, v223, v52
	ds_read_b64_tr_b16 v[56:57], v83 offset:32768
	ds_read_b64_tr_b16 v[58:59], v83 offset:33280
	v_exp_f32_e32 v82, v65
	s_waitcnt lgkmcnt(0)
	v_mfma_f32_32x32x16_bf16 v[36:51], v[52:55], v[56:59], v[36:51]
	v_cvt_pk_bf16_f32 v60, v70, v60
	ds_read_b64_tr_b16 v[68:69], v83 offset:33792
	ds_read_b64_tr_b16 v[70:71], v83 offset:34304
	v_cvt_pk_bf16_f32 v61, v61, v62
	v_cvt_pk_bf16_f32 v62, v63, v64
	v_cvt_pk_bf16_f32 v63, v79, v82
	v_sub_f32_e32 v75, v67, v225
	v_cvt_pk_bf16_f32 v56, v236, v2
	s_waitcnt lgkmcnt(0)
	v_mfma_f32_32x32x16_bf16 v[36:51], v[60:63], v[68:71], v[36:51]
	v_cvt_pk_bf16_f32 v57, v237, v226
	v_cvt_pk_bf16_f32 v58, v227, v228
	v_cvt_pk_bf16_f32 v59, v229, v72
	ds_read_b64_tr_b16 v[64:65], v83 offset:34816
	ds_read_b64_tr_b16 v[66:67], v83 offset:35328
	v_exp_f32_e32 v80, v75
	v_cvt_pk_bf16_f32 v68, v73, v74
	ds_read_b64_tr_b16 v[72:73], v83 offset:35840
	ds_read_b64_tr_b16 v[74:75], v83 offset:36352
	s_waitcnt lgkmcnt(2)
	v_mfma_f32_32x32x16_bf16 v[36:51], v[56:59], v[64:67], v[36:51]
	v_cvt_pk_bf16_f32 v69, v238, v76
	v_cvt_pk_bf16_f32 v70, v77, v78
	v_cvt_pk_bf16_f32 v71, v239, v80
	s_waitcnt lgkmcnt(0)
	s_nop 0
	v_mfma_f32_32x32x16_bf16 v[36:51], v[68:71], v[72:75], v[36:51]
	ds_read_b64_tr_b16 v[64:65], v83 offset:36864
	ds_read_b64_tr_b16 v[66:67], v83 offset:37376
	ds_read_b64_tr_b16 v[72:73], v83 offset:37888
	ds_read_b64_tr_b16 v[74:75], v83 offset:38400
	s_waitcnt lgkmcnt(2)
	v_mfma_f32_32x32x16_bf16 v[18:33], v[52:55], v[64:67], v[18:33]
	s_waitcnt lgkmcnt(0)
	v_mfma_f32_32x32x16_bf16 v[18:33], v[60:63], v[72:75], v[18:33]
	ds_read_b64_tr_b16 v[52:53], v83 offset:38912
	ds_read_b64_tr_b16 v[54:55], v83 offset:39424
	ds_read_b64_tr_b16 v[60:61], v83 offset:39936
	ds_read_b64_tr_b16 v[62:63], v83 offset:40448
	v_add_f32_e32 v83, v79, v239
	s_waitcnt lgkmcnt(2)
	v_mfma_f32_32x32x16_bf16 v[18:33], v[56:59], v[52:55], v[18:33]
	v_add_f32_e64 v52, v82, v80
	v_add_f32_e64 v53, v83, v81
	v_add_f32_e32 v2, v52, v53
	v_add_f32_e32 v210, v210, v2
	s_waitcnt lgkmcnt(0)
	v_mfma_f32_32x32x16_bf16 v[18:33], v[68:71], v[60:63], v[18:33]
	s_cmp_eq_u32 s82, 0xff880000
	s_cbranch_scc1 .LBB0_781

; #define LAS __attribute__((address_space(3)))
; template <int KIND>
; __device__ __forceinline__ void sample_unit(const AttnCtx& C, int u, LAS unsigned char* lds) {
;     ...
;     if (kp == 0) {
; #pragma unroll
;         for (int k = 0; k < TPS - 1; ++k) {
;             const LAS float* ps = (const LAS float*)(lds + (size_t)(grp * (TPS - 1) + k) * PST);
;             const float mb = ps[NDB * 16 * 64 + lane], lb = ps[NDB * 16 * 64 + 64 + lane];
;             const float mt = fmaxf(m_run, mb); const float wa = __builtin_amdgcn_exp2f(m_run - mt), wb = __builtin_amdgcn_exp2f(mb - mt);
;             l_run = l_run * wa + lb * wb; m_run = mt;
;             if (hi == 0) { wsf[r32] = wa; wsf[32 + r32] = wb; }
; #pragma unroll
;             for (int gq = 0; gq < 4; ++gq) { const f32x4 a = *(const LAS f32x4*)(wsf + 8 * gq + 4 * hi), bq = *(const LAS f32x4*)(wsf + 32 + 8 * gq + 4 * hi);
; #pragma unroll
;                 for (int d = 0; d < NDB; ++d)
; #pragma unroll
;                     for (int e = 0; e < 4; ++e) { const int r = 4 * gq + e; o[d][r] = o[d][r] * a[e] + ps[(d * 16 + r) * 64 + lane] * bq[e]; } }
;         }
;         const float lt = l_run + __shfl_xor(l_run, 32);
;         if (hi == 0) wsf[r32] = 1.0f / lt;
;     }
.LBB0_794:
	s_or_b64 exec, exec, s[6:7]
	v_pk_mul_f32 v[228:229], v[128:129], v[228:229]
	v_pk_mul_f32 v[128:129], v[128:129], v[226:227]
	v_pk_fma_f32 v[36:37], v[36:37], v[124:125], v[228:229]
	v_pk_fma_f32 v[18:19], v[18:19], v[124:125], v[128:129]
	v_pk_mul_f32 v[124:125], v[130:131], v[222:223]
	s_waitcnt lgkmcnt(0)
	v_mul_f32_e32 v1, v74, v144
	v_pk_fma_f32 v[20:21], v[20:21], v[126:127], v[124:125]
	v_pk_mul_f32 v[124:125], v[104:105], v[202:203]
	v_pk_mul_f32 v[104:105], v[104:105], v[172:173]
	v_pk_fma_f32 v[40:41], v[40:41], v[84:85], v[124:125]
	v_pk_fma_f32 v[22:23], v[22:23], v[84:85], v[104:105]
	v_pk_mul_f32 v[84:85], v[106:107], v[164:165]
	v_mul_f32_e32 v2, v75, v145
	v_pk_fma_f32 v[24:25], v[24:25], v[86:87], v[84:85]
	v_pk_mul_f32 v[84:85], v[112:113], v[208:209]
	v_fmac_f32_e32 v1, v50, v66
	v_pk_fma_f32 v[44:45], v[44:45], v[88:89], v[84:85]
	v_pk_mul_f32 v[84:85], v[114:115], v[188:189]
	v_fmac_f32_e32 v2, v51, v67
	v_pk_fma_f32 v[46:47], v[46:47], v[90:91], v[84:85]
	v_pk_mul_f32 v[84:85], v[112:113], v[196:197]
	v_pk_mul_f32 v[50:51], v[72:73], v[148:149]
	v_pk_fma_f32 v[26:27], v[26:27], v[88:89], v[84:85]
	v_pk_mul_f32 v[84:85], v[114:115], v[182:183]
	v_pk_fma_f32 v[30:31], v[30:31], v[64:65], v[50:51]
	v_pk_fma_f32 v[28:29], v[28:29], v[90:91], v[84:85]
	v_pk_mul_f32 v[84:85], v[72:73], v[154:155]
	v_pk_mul_f32 v[224:225], v[130:131], v[224:225]
	v_pk_fma_f32 v[48:49], v[48:49], v[64:65], v[84:85]
	v_mul_f32_e32 v64, v74, v136
	v_mul_f32_e32 v65, v75, v137
	v_fmac_f32_e32 v64, v32, v66
	v_fmac_f32_e32 v65, v33, v67
	v_pk_mul_f32 v[32:33], v[100:101], v[200:201]
	v_pk_fma_f32 v[38:39], v[38:39], v[126:127], v[224:225]
	v_pk_fma_f32 v[32:33], v[36:37], v[96:97], v[32:33]
	v_pk_mul_f32 v[36:37], v[102:103], v[180:181]
	v_pk_mul_f32 v[124:125], v[106:107], v[184:185]
	v_pk_fma_f32 v[38:39], v[38:39], v[98:99], v[36:37]
	v_pk_mul_f32 v[36:37], v[100:101], v[186:187]
	v_pk_fma_f32 v[42:43], v[42:43], v[86:87], v[124:125]
	v_pk_fma_f32 v[18:19], v[18:19], v[96:97], v[36:37]
	v_pk_mul_f32 v[36:37], v[102:103], v[168:169]
	v_pk_mul_f32 v[50:51], v[76:77], v[146:147]
	v_pk_fma_f32 v[20:21], v[20:21], v[98:99], v[36:37]
	v_pk_mul_f32 v[36:37], v[92:93], v[158:159]
	v_mov_b32_e32 v90, v55
	v_pk_fma_f32 v[40:41], v[40:41], v[56:57], v[36:37]
	v_pk_mul_f32 v[36:37], v[94:95], v[152:153]
	v_mov_b32_e32 v91, v63
	v_pk_fma_f32 v[42:43], v[42:43], v[58:59], v[36:37]
	v_pk_mul_f32 v[36:37], v[92:93], v[156:157]
	v_pk_fma_f32 v[30:31], v[30:31], v[68:69], v[50:51]
	v_pk_fma_f32 v[22:23], v[22:23], v[56:57], v[36:37]
	v_pk_mul_f32 v[36:37], v[94:95], v[150:151]
	v_mul_f32_e32 v56, v79, v139
	v_pk_fma_f32 v[24:25], v[24:25], v[58:59], v[36:37]
	v_pk_mul_f32 v[36:37], v[108:109], v[178:179]
	v_fmac_f32_e32 v56, v65, v71
	v_pk_fma_f32 v[44:45], v[44:45], v[80:81], v[36:37]
	v_pk_mul_f32 v[36:37], v[110:111], v[160:161]
	v_pk_mul_f32 v[50:51], v[120:121], v[218:219]
	v_pk_fma_f32 v[46:47], v[46:47], v[82:83], v[36:37]
	v_pk_mul_f32 v[36:37], v[108:109], v[170:171]
	v_mov_b32_e32 v57, v17
	v_pk_fma_f32 v[26:27], v[26:27], v[80:81], v[36:37]
	v_pk_mul_f32 v[36:37], v[110:111], v[162:163]
	v_pk_mul_f32 v[58:59], v[122:123], v[206:207]
	v_pk_fma_f32 v[28:29], v[28:29], v[82:83], v[36:37]
	v_pk_mul_f32 v[36:37], v[76:77], v[142:143]
	v_pk_mul_f32 v[66:67], v[122:123], v[204:205]
	v_pk_fma_f32 v[48:49], v[48:49], v[68:69], v[36:37]
	v_mul_f32_e32 v37, v78, v140
	v_fmac_f32_e32 v37, v1, v70
	v_mul_f32_e32 v36, v79, v141
	v_fmac_f32_e32 v36, v2, v71
	v_mul_f32_e32 v1, v78, v138
	v_mul_f32_e32 v86, v37, v54
	v_mov_b32_e32 v37, v193
	v_fmac_f32_e32 v1, v64, v70
	v_pk_mul_f32 v[36:37], v[36:37], v[90:91]
	v_pk_mul_f32 v[64:65], v[120:121], v[214:215]
	v_mov_b32_e32 v87, v36
	v_mov_b32_e32 v89, v37
	v_pk_fma_f32 v[36:37], v[32:33], v[8:9], v[50:51]
	v_pk_mul_f32 v[32:33], v[60:61], v[34:35]
	v_mul_f32_e32 v34, v1, v54
	v_pk_mul_f32 v[54:55], v[56:57], v[90:91]
	v_pk_mul_f32 v[68:69], v[116:117], v[190:191]
	v_pk_mul_f32 v[70:71], v[118:119], v[166:167]
	v_pk_mul_f32 v[72:73], v[116:117], v[176:177]
	v_pk_mul_f32 v[74:75], v[118:119], v[174:175]
	v_pk_mul_f32 v[76:77], v[132:133], v[220:221]
	v_pk_mul_f32 v[78:79], v[134:135], v[212:213]
	v_pk_mul_f32 v[80:81], v[132:133], v[216:217]
	v_pk_mul_f32 v[82:83], v[134:135], v[210:211]
	v_pk_mul_f32 v[84:85], v[60:61], v[194:195]
	v_mul_f32_e32 v88, v62, v192
	v_mul_f32_e32 v16, v62, v16
	v_mov_b32_e32 v35, v54
	v_mov_b32_e32 v17, v55
	v_pk_fma_f32 v[38:39], v[38:39], v[10:11], v[58:59]
	v_pk_fma_f32 v[40:41], v[40:41], v[4:5], v[68:69]
	v_pk_fma_f32 v[42:43], v[42:43], v[6:7], v[70:71]
	v_pk_fma_f32 v[44:45], v[44:45], v[12:13], v[76:77]
	v_pk_fma_f32 v[46:47], v[46:47], v[14:15], v[78:79]
	v_pk_fma_f32 v[48:49], v[48:49], v[52:53], v[84:85]
	v_add_f32_e32 v50, v86, v88
	v_add_f32_e32 v51, v87, v89
	v_pk_fma_f32 v[18:19], v[18:19], v[8:9], v[64:65]
	v_pk_fma_f32 v[20:21], v[20:21], v[10:11], v[66:67]
	v_pk_fma_f32 v[22:23], v[22:23], v[4:5], v[72:73]
	v_pk_fma_f32 v[24:25], v[24:25], v[6:7], v[74:75]
	v_pk_fma_f32 v[26:27], v[26:27], v[12:13], v[80:81]
	v_pk_fma_f32 v[28:29], v[28:29], v[14:15], v[82:83]
	v_pk_fma_f32 v[30:31], v[30:31], v[52:53], v[32:33]
	v_add_f32_e32 v32, v34, v16
	v_add_f32_e32 v33, v35, v17
